# prep transpose loops (w_in, sample V^T caches): next tile's global load prefetched, 2-way unrolled
# baseline (speedup 1.0000x reference)
.Lpf2_768_topP:
	s_ashr_i32 s6, s49, 7
	s_ashr_i32 s7, s6, 31
	s_and_b32 s50, s49, 0x60
	s_lshl_b64 s[24:25], s[6:7], 20
	s_add_u32 s24, s46, s24
	s_addc_u32 s25, s47, s25
	s_and_b32 s7, s48, 0x7c0
	s_lshl_b32 s0, s50, 2
	v_readlane_b32 s71, v253, 50
	v_readlane_b32 s70, v253, 7
	s_add_i32 s71, s49, s71
	s_add_i32 s70, s48, s70
	s_cmpk_gt_i32 s71, 0x3ff
	s_cbranch_scc1 .Lpf2_768_nopfP
	s_mov_b32 s65, s1
	s_ashr_i32 s66, s71, 7
	s_ashr_i32 s67, s66, 31
	s_and_b32 s72, s71, 0x60
	s_lshl_b64 s[68:69], s[66:67], 20
	s_add_u32 s68, s46, s68
	s_addc_u32 s69, s47, s69
	s_and_b32 s67, s70, 0x7c0
	v_add_u32_e32 v108, s67, v11
	v_ashrrev_i32_e32 v109, 31, v108
	v_lshlrev_b64 v[108:109], 9, v[108:109]
	v_lshl_add_u64 v[108:109], s[68:69], 0, v[108:109]
	s_lshl_b32 s64, s72, 2
	v_lshl_add_u64 v[108:109], v[108:109], 0, s[64:65]
	v_lshl_add_u64 v[108:109], v[108:109], 0, v[0:1]
	global_load_dwordx4 v[104:107], v[108:109], off
	s_waitcnt vmcnt(1)
	s_branch .Lpf2_768_goP

.Lpf2_768_latchP:
	s_or_b64 exec, exec, s[24:25]
	s_mov_b32 s49, s71
	s_mov_b32 s48, s70
	s_cmpk_gt_i32 s49, 0x3ff
	s_barrier
	v_readlane_b32 s7, v253, 51
	s_cbranch_scc1 .LBB0_770
.Lpf2_768_topQ:
	s_ashr_i32 s6, s49, 7
	s_ashr_i32 s7, s6, 31
	s_and_b32 s50, s49, 0x60
	s_lshl_b64 s[24:25], s[6:7], 20
	s_add_u32 s24, s46, s24
	s_addc_u32 s25, s47, s25
	s_and_b32 s7, s48, 0x7c0
	s_lshl_b32 s0, s50, 2
	v_readlane_b32 s71, v253, 50
	v_readlane_b32 s70, v253, 7
	s_add_i32 s71, s49, s71
	s_add_i32 s70, s48, s70
	s_cmpk_gt_i32 s71, 0x3ff
	s_cbranch_scc1 .Lpf2_768_nopfQ
	s_mov_b32 s65, s1
	s_ashr_i32 s66, s71, 7
	s_ashr_i32 s67, s66, 31
	s_and_b32 s72, s71, 0x60
	s_lshl_b64 s[68:69], s[66:67], 20
	s_add_u32 s68, s46, s68
	s_addc_u32 s69, s47, s69
	s_and_b32 s67, s70, 0x7c0
	v_add_u32_e32 v108, s67, v11
	v_ashrrev_i32_e32 v109, 31, v108
	v_lshlrev_b64 v[108:109], 9, v[108:109]
	v_lshl_add_u64 v[108:109], s[68:69], 0, v[108:109]
	s_lshl_b32 s64, s72, 2
	v_lshl_add_u64 v[108:109], v[108:109], 0, s[64:65]
	v_lshl_add_u64 v[108:109], v[108:109], 0, v[0:1]
	global_load_dwordx4 v[100:103], v[108:109], off
	s_waitcnt vmcnt(1)
	s_branch .Lpf2_768_goQ

.Lpf2_768_latchQ:
	s_or_b64 exec, exec, s[24:25]
	s_mov_b32 s49, s71
	s_mov_b32 s48, s70
	s_cmpk_gt_i32 s49, 0x3ff
	s_barrier
	v_readlane_b32 s7, v253, 51
	s_cbranch_scc1 .LBB0_770
	s_branch .Lpf2_768_topP

.Lpf1_773_topP:
	s_ashr_i32 s14, s51, 9
	s_ashr_i32 s15, s14, 31
	s_and_b32 s52, s51, 0x1e0
	s_lshl_b64 s[46:47], s[14:15], 22
	s_add_u32 s46, s48, s46
	s_addc_u32 s47, s49, s47
	s_and_b32 s15, s50, 0x7c0
	s_lshl_b32 s0, s52, 2
	v_readlane_b32 s71, v253, 50
	v_readlane_b32 s70, v253, 7
	s_add_i32 s71, s51, s71
	s_add_i32 s70, s50, s70
	s_cmpk_gt_i32 s71, 0xfff
	s_cbranch_scc1 .Lpf1_773_nopfP
	s_mov_b32 s65, s1
	s_ashr_i32 s66, s71, 9
	s_ashr_i32 s67, s66, 31
	s_and_b32 s72, s71, 0x1e0
	s_lshl_b64 s[68:69], s[66:67], 22
	s_add_u32 s68, s48, s68
	s_addc_u32 s69, s49, s69
	s_and_b32 s67, s70, 0x7c0
	v_add_u32_e32 v108, s67, v11
	v_ashrrev_i32_e32 v109, 31, v108
	v_lshlrev_b64 v[108:109], 11, v[108:109]
	v_lshl_add_u64 v[108:109], s[68:69], 0, v[108:109]
	s_lshl_b32 s64, s72, 2
	v_lshl_add_u64 v[108:109], v[108:109], 0, s[64:65]
	v_lshl_add_u64 v[108:109], v[108:109], 0, v[0:1]
	global_load_dwordx4 v[104:107], v[108:109], off
	s_waitcnt vmcnt(1)
	s_branch .Lpf1_773_goP

.Lpf1_773_latchP:
	s_or_b64 exec, exec, s[46:47]
	s_mov_b32 s51, s71
	s_mov_b32 s50, s70
	s_cmpk_gt_i32 s51, 0xfff
	s_barrier
	v_readlane_b32 s15, v253, 51
	s_cbranch_scc1 .LBB0_775
.Lpf1_773_topQ:
	s_ashr_i32 s14, s51, 9
	s_ashr_i32 s15, s14, 31
	s_and_b32 s52, s51, 0x1e0
	s_lshl_b64 s[46:47], s[14:15], 22
	s_add_u32 s46, s48, s46
	s_addc_u32 s47, s49, s47
	s_and_b32 s15, s50, 0x7c0
	s_lshl_b32 s0, s52, 2
	v_readlane_b32 s71, v253, 50
	v_readlane_b32 s70, v253, 7
	s_add_i32 s71, s51, s71
	s_add_i32 s70, s50, s70
	s_cmpk_gt_i32 s71, 0xfff
	s_cbranch_scc1 .Lpf1_773_nopfQ
	s_mov_b32 s65, s1
	s_ashr_i32 s66, s71, 9
	s_ashr_i32 s67, s66, 31
	s_and_b32 s72, s71, 0x1e0
	s_lshl_b64 s[68:69], s[66:67], 22
	s_add_u32 s68, s48, s68
	s_addc_u32 s69, s49, s69
	s_and_b32 s67, s70, 0x7c0
	v_add_u32_e32 v108, s67, v11
	v_ashrrev_i32_e32 v109, 31, v108
	v_lshlrev_b64 v[108:109], 11, v[108:109]
	v_lshl_add_u64 v[108:109], s[68:69], 0, v[108:109]
	s_lshl_b32 s64, s72, 2
	v_lshl_add_u64 v[108:109], v[108:109], 0, s[64:65]
	v_lshl_add_u64 v[108:109], v[108:109], 0, v[0:1]
	global_load_dwordx4 v[100:103], v[108:109], off
	s_waitcnt vmcnt(1)
	s_branch .Lpf1_773_goQ

.Lpf1_773_latchQ:
	s_or_b64 exec, exec, s[46:47]
	s_mov_b32 s51, s71
	s_mov_b32 s50, s70
	s_cmpk_gt_i32 s51, 0xfff
	s_barrier
	v_readlane_b32 s15, v253, 51
	s_cbranch_scc1 .LBB0_775
	s_branch .Lpf1_773_topP
